# LN-stat and sum-of-squares row reductions use v_permlane16/32_swap instead of ds_bpermute (bit-identical sums)
# baseline (speedup 1.0000x reference)
.LBB0_276:
	v_add_co_u32_e32 v126, vcc, 0x8000, v146
	v_cvt_pk_bf16_f32 v112, v122, v123
	v_cvt_pk_bf16_f32 v113, v124, v125
	v_cvt_pk_bf16_f32 v114, v116, v117
	v_cvt_pk_bf16_f32 v115, v118, v119
	s_nop 1
	v_addc_co_u32_e32 v127, vcc, 0, v147, vcc
	s_and_b64 vcc, exec, s[0:1]
	global_store_dwordx4 v[126:127], v[112:115], off
	s_cbranch_vccnz .LBB0_280
	s_nop 0
	v_add_f32_e32 v112, v122, v123
	v_add_f32_e32 v113, v124, v125
	v_add_f32_e32 v112, v112, v113
	v_add_f32_e32 v113, v116, v117
	v_add_f32_e32 v112, v112, v113
	v_add_f32_e32 v113, v118, v119
	v_add_f32_e32 v112, v113, v112
	v_mul_f32_e32 v113, v123, v123
	v_mul_f32_e32 v114, v125, v125
	v_fmac_f32_e32 v113, v122, v122
	v_fmac_f32_e32 v114, v124, v124
	v_add_f32_e32 v113, v113, v114
	v_mul_f32_e32 v114, v117, v117
	v_fmac_f32_e32 v114, v116, v116
	v_add_f32_e32 v113, v113, v114
	v_mul_f32_e32 v114, v119, v119
	v_fmac_f32_e32 v114, v118, v118
	v_add_f32_e32 v113, v114, v113
	v_add_f32_e32 v112, v120, v112
	v_add_f32_e32 v115, v121, v113
	v_mov_b32_e32 v114, v112
	s_nop 1
	v_permlane16_swap_b32_e32 v114, v112
	s_nop 0
	v_mov_b32_e32 v116, v115
	s_nop 1
	v_permlane16_swap_b32_e32 v116, v115
	s_nop 0
	s_waitcnt lgkmcnt(0)
	v_add_f32_e32 v112, v112, v114
	v_add_f32_e32 v114, v115, v116
	v_mov_b32_e32 v113, v112
	s_nop 1
	v_permlane32_swap_b32_e32 v113, v112
	s_nop 0
	v_mov_b32_e32 v115, v114
	s_nop 1
	v_permlane32_swap_b32_e32 v115, v114
	s_nop 0
	s_and_saveexec_b64 s[0:1], s[4:5]
	s_cbranch_execz .LBB0_279
	s_waitcnt lgkmcnt(0)
	v_add_f32_e32 v114, v114, v115
	v_add_f32_e32 v115, v112, v113
	v_add_u32_e32 v112, s24, v164
	v_ashrrev_i32_e32 v113, 31, v112
	v_lshl_add_u64 v[112:113], v[112:113], 3, s[72:73]
	global_atomic_add_f32 v[112:113], v115, off
	global_atomic_add_f32 v[112:113], v114, off offset:4

.LBB0_313:
	v_add_co_u32_e32 v110, vcc, 0x8000, v114
	v_cvt_pk_bf16_f32 v96, v106, v107
	v_cvt_pk_bf16_f32 v97, v108, v109
	v_cvt_pk_bf16_f32 v98, v100, v101
	v_cvt_pk_bf16_f32 v99, v102, v103
	s_nop 1
	v_addc_co_u32_e32 v111, vcc, 0, v115, vcc
	s_and_b64 vcc, exec, s[0:1]
	global_store_dwordx4 v[110:111], v[96:99], off
	s_cbranch_vccnz .LBB0_317
	s_nop 0
	v_add_f32_e32 v96, v106, v107
	v_add_f32_e32 v97, v108, v109
	v_add_f32_e32 v96, v96, v97
	v_add_f32_e32 v97, v100, v101
	v_add_f32_e32 v96, v96, v97
	v_add_f32_e32 v97, v102, v103
	v_add_f32_e32 v96, v97, v96
	v_mul_f32_e32 v97, v107, v107
	v_mul_f32_e32 v98, v109, v109
	v_fmac_f32_e32 v97, v106, v106
	v_fmac_f32_e32 v98, v108, v108
	v_add_f32_e32 v97, v97, v98
	v_mul_f32_e32 v98, v101, v101
	v_fmac_f32_e32 v98, v100, v100
	v_add_f32_e32 v97, v97, v98
	v_mul_f32_e32 v98, v103, v103
	v_fmac_f32_e32 v98, v102, v102
	v_add_f32_e32 v97, v98, v97
	v_add_f32_e32 v96, v104, v96
	v_add_f32_e32 v99, v105, v97
	v_mov_b32_e32 v98, v96
	s_nop 1
	v_permlane16_swap_b32_e32 v98, v96
	s_nop 0
	v_mov_b32_e32 v100, v99
	s_nop 1
	v_permlane16_swap_b32_e32 v100, v99
	s_nop 0
	s_waitcnt lgkmcnt(0)
	v_add_f32_e32 v96, v96, v98
	v_add_f32_e32 v98, v99, v100
	v_mov_b32_e32 v97, v96
	s_nop 1
	v_permlane32_swap_b32_e32 v97, v96
	s_nop 0
	v_mov_b32_e32 v99, v98
	s_nop 1
	v_permlane32_swap_b32_e32 v99, v98
	s_nop 0
	s_and_saveexec_b64 s[0:1], s[4:5]
	s_cbranch_execz .LBB0_316
	s_waitcnt lgkmcnt(0)
	v_add_f32_e32 v98, v98, v99
	v_add_f32_e32 v99, v96, v97
	v_add_u32_e32 v96, s24, v126
	v_ashrrev_i32_e32 v97, 31, v96
	v_lshl_add_u64 v[96:97], v[96:97], 3, s[72:73]
	global_atomic_add_f32 v[96:97], v99, off
	global_atomic_add_f32 v[96:97], v98, off offset:4

.LBB0_350:
	v_add_co_u32_e32 v94, vcc, 0x8000, v98
	v_cvt_pk_bf16_f32 v80, v90, v91
	v_cvt_pk_bf16_f32 v81, v92, v93
	v_cvt_pk_bf16_f32 v82, v84, v85
	v_cvt_pk_bf16_f32 v83, v86, v87
	s_nop 1
	v_addc_co_u32_e32 v95, vcc, 0, v99, vcc
	s_and_b64 vcc, exec, s[0:1]
	global_store_dwordx4 v[94:95], v[80:83], off
	s_cbranch_vccnz .LBB0_354
	s_nop 0
	v_add_f32_e32 v80, v90, v91
	v_add_f32_e32 v81, v92, v93
	v_add_f32_e32 v80, v80, v81
	v_add_f32_e32 v81, v84, v85
	v_add_f32_e32 v80, v80, v81
	v_add_f32_e32 v81, v86, v87
	v_add_f32_e32 v80, v81, v80
	v_mul_f32_e32 v81, v91, v91
	v_mul_f32_e32 v82, v93, v93
	v_fmac_f32_e32 v81, v90, v90
	v_fmac_f32_e32 v82, v92, v92
	v_add_f32_e32 v81, v81, v82
	v_mul_f32_e32 v82, v85, v85
	v_fmac_f32_e32 v82, v84, v84
	v_add_f32_e32 v81, v81, v82
	v_mul_f32_e32 v82, v87, v87
	v_fmac_f32_e32 v82, v86, v86
	v_add_f32_e32 v81, v82, v81
	v_add_f32_e32 v80, v88, v80
	v_add_f32_e32 v83, v89, v81
	v_mov_b32_e32 v82, v80
	s_nop 1
	v_permlane16_swap_b32_e32 v82, v80
	s_nop 0
	v_mov_b32_e32 v84, v83
	s_nop 1
	v_permlane16_swap_b32_e32 v84, v83
	s_nop 0
	s_waitcnt lgkmcnt(0)
	v_add_f32_e32 v80, v80, v82
	v_add_f32_e32 v82, v83, v84
	v_mov_b32_e32 v81, v80
	s_nop 1
	v_permlane32_swap_b32_e32 v81, v80
	s_nop 0
	v_mov_b32_e32 v83, v82
	s_nop 1
	v_permlane32_swap_b32_e32 v83, v82
	s_nop 0
	s_and_saveexec_b64 s[0:1], s[4:5]
	s_cbranch_execz .LBB0_353
	s_waitcnt lgkmcnt(0)
	v_add_f32_e32 v82, v82, v83
	v_add_f32_e32 v83, v80, v81
	v_add_u32_e32 v80, s24, v110
	v_ashrrev_i32_e32 v81, 31, v80
	v_lshl_add_u64 v[80:81], v[80:81], 3, s[72:73]
	global_atomic_add_f32 v[80:81], v83, off
	global_atomic_add_f32 v[80:81], v82, off offset:4

.LBB0_387:
	v_add_co_u32_e32 v78, vcc, 0x8000, v82
	v_cvt_pk_bf16_f32 v64, v74, v75
	v_cvt_pk_bf16_f32 v65, v76, v77
	v_cvt_pk_bf16_f32 v66, v68, v69
	v_cvt_pk_bf16_f32 v67, v70, v71
	s_nop 1
	v_addc_co_u32_e32 v79, vcc, 0, v83, vcc
	s_and_b64 vcc, exec, s[0:1]
	global_store_dwordx4 v[78:79], v[64:67], off
	s_cbranch_vccnz .LBB0_391
	s_nop 0
	v_add_f32_e32 v64, v74, v75
	v_add_f32_e32 v65, v76, v77
	v_add_f32_e32 v64, v64, v65
	v_add_f32_e32 v65, v68, v69
	v_add_f32_e32 v64, v64, v65
	v_add_f32_e32 v65, v70, v71
	v_add_f32_e32 v64, v65, v64
	v_mul_f32_e32 v65, v75, v75
	v_mul_f32_e32 v66, v77, v77
	v_fmac_f32_e32 v65, v74, v74
	v_fmac_f32_e32 v66, v76, v76
	v_add_f32_e32 v65, v65, v66
	v_mul_f32_e32 v66, v69, v69
	v_fmac_f32_e32 v66, v68, v68
	v_add_f32_e32 v65, v65, v66
	v_mul_f32_e32 v66, v71, v71
	v_fmac_f32_e32 v66, v70, v70
	v_add_f32_e32 v65, v66, v65
	v_add_f32_e32 v64, v72, v64
	v_add_f32_e32 v67, v73, v65
	v_mov_b32_e32 v66, v64
	s_nop 1
	v_permlane16_swap_b32_e32 v66, v64
	s_nop 0
	v_mov_b32_e32 v68, v67
	s_nop 1
	v_permlane16_swap_b32_e32 v68, v67
	s_nop 0
	s_waitcnt lgkmcnt(0)
	v_add_f32_e32 v64, v64, v66
	v_add_f32_e32 v66, v67, v68
	v_mov_b32_e32 v65, v64
	s_nop 1
	v_permlane32_swap_b32_e32 v65, v64
	s_nop 0
	v_mov_b32_e32 v67, v66
	s_nop 1
	v_permlane32_swap_b32_e32 v67, v66
	s_nop 0
	s_and_saveexec_b64 s[0:1], s[4:5]
	s_cbranch_execz .LBB0_390
	s_waitcnt lgkmcnt(0)
	v_add_f32_e32 v66, v66, v67
	v_add_f32_e32 v67, v64, v65
	v_add_u32_e32 v64, s24, v94
	v_ashrrev_i32_e32 v65, 31, v64
	v_lshl_add_u64 v[64:65], v[64:65], 3, s[72:73]
	global_atomic_add_f32 v[64:65], v67, off
	global_atomic_add_f32 v[64:65], v66, off offset:4

.LBB0_425:
	v_add_co_u32_e32 v62, vcc, 0x8000, v66
	v_cvt_pk_bf16_f32 v48, v58, v59
	v_cvt_pk_bf16_f32 v49, v60, v61
	v_cvt_pk_bf16_f32 v50, v52, v53
	v_cvt_pk_bf16_f32 v51, v54, v55
	s_nop 1
	v_addc_co_u32_e32 v63, vcc, 0, v67, vcc
	s_and_b64 vcc, exec, s[0:1]
	global_store_dwordx4 v[62:63], v[48:51], off
	s_cbranch_vccnz .LBB0_429
	s_nop 0
	v_add_f32_e32 v48, v58, v59
	v_add_f32_e32 v49, v60, v61
	v_add_f32_e32 v48, v48, v49
	v_add_f32_e32 v49, v52, v53
	v_add_f32_e32 v48, v48, v49
	v_add_f32_e32 v49, v54, v55
	v_add_f32_e32 v48, v49, v48
	v_mul_f32_e32 v49, v59, v59
	v_mul_f32_e32 v50, v61, v61
	v_fmac_f32_e32 v49, v58, v58
	v_fmac_f32_e32 v50, v60, v60
	v_add_f32_e32 v49, v49, v50
	v_mul_f32_e32 v50, v53, v53
	v_fmac_f32_e32 v50, v52, v52
	v_add_f32_e32 v49, v49, v50
	v_mul_f32_e32 v50, v55, v55
	v_fmac_f32_e32 v50, v54, v54
	v_add_f32_e32 v49, v50, v49
	v_add_f32_e32 v48, v56, v48
	v_add_f32_e32 v51, v57, v49
	v_mov_b32_e32 v50, v48
	s_nop 1
	v_permlane16_swap_b32_e32 v50, v48
	s_nop 0
	v_mov_b32_e32 v52, v51
	s_nop 1
	v_permlane16_swap_b32_e32 v52, v51
	s_nop 0
	s_waitcnt lgkmcnt(0)
	v_add_f32_e32 v48, v48, v50
	v_add_f32_e32 v50, v51, v52
	v_mov_b32_e32 v49, v48
	s_nop 1
	v_permlane32_swap_b32_e32 v49, v48
	s_nop 0
	v_mov_b32_e32 v51, v50
	s_nop 1
	v_permlane32_swap_b32_e32 v51, v50
	s_nop 0
	s_and_saveexec_b64 s[0:1], s[4:5]
	s_cbranch_execz .LBB0_428
	s_waitcnt lgkmcnt(0)
	v_add_f32_e32 v50, v50, v51
	v_add_f32_e32 v51, v48, v49
	v_add_u32_e32 v48, s21, v164
	v_ashrrev_i32_e32 v49, 31, v48
	v_lshl_add_u64 v[48:49], v[48:49], 3, s[72:73]
	global_atomic_add_f32 v[48:49], v51, off
	global_atomic_add_f32 v[48:49], v50, off offset:4

.LBB0_462:
	v_add_co_u32_e32 v46, vcc, 0x8000, v48
	v_cvt_pk_bf16_f32 v32, v42, v43
	v_cvt_pk_bf16_f32 v33, v44, v45
	v_cvt_pk_bf16_f32 v34, v36, v37
	v_cvt_pk_bf16_f32 v35, v38, v39
	s_nop 1
	v_addc_co_u32_e32 v47, vcc, 0, v49, vcc
	s_and_b64 vcc, exec, s[0:1]
	global_store_dwordx4 v[46:47], v[32:35], off
	s_cbranch_vccnz .LBB0_466
	s_nop 0
	v_add_f32_e32 v32, v42, v43
	v_add_f32_e32 v33, v44, v45
	v_add_f32_e32 v32, v32, v33
	v_add_f32_e32 v33, v36, v37
	v_add_f32_e32 v32, v32, v33
	v_add_f32_e32 v33, v38, v39
	v_add_f32_e32 v32, v33, v32
	v_mul_f32_e32 v33, v43, v43
	v_mul_f32_e32 v34, v45, v45
	v_fmac_f32_e32 v33, v42, v42
	v_fmac_f32_e32 v34, v44, v44
	v_add_f32_e32 v33, v33, v34
	v_mul_f32_e32 v34, v37, v37
	v_fmac_f32_e32 v34, v36, v36
	v_add_f32_e32 v33, v33, v34
	v_mul_f32_e32 v34, v39, v39
	v_fmac_f32_e32 v34, v38, v38
	v_add_f32_e32 v33, v34, v33
	v_add_f32_e32 v32, v40, v32
	v_add_f32_e32 v35, v41, v33
	v_mov_b32_e32 v34, v32
	s_nop 1
	v_permlane16_swap_b32_e32 v34, v32
	s_nop 0
	v_mov_b32_e32 v36, v35
	s_nop 1
	v_permlane16_swap_b32_e32 v36, v35
	s_nop 0
	s_waitcnt lgkmcnt(0)
	v_add_f32_e32 v32, v32, v34
	v_add_f32_e32 v34, v35, v36
	v_mov_b32_e32 v33, v32
	s_nop 1
	v_permlane32_swap_b32_e32 v33, v32
	s_nop 0
	v_mov_b32_e32 v35, v34
	s_nop 1
	v_permlane32_swap_b32_e32 v35, v34
	s_nop 0
	s_and_saveexec_b64 s[0:1], s[4:5]
	s_cbranch_execz .LBB0_465
	s_waitcnt lgkmcnt(0)
	v_add_f32_e32 v34, v34, v35
	v_add_f32_e32 v35, v32, v33
	v_add_u32_e32 v32, s21, v126
	v_ashrrev_i32_e32 v33, 31, v32
	v_lshl_add_u64 v[32:33], v[32:33], 3, s[72:73]
	global_atomic_add_f32 v[32:33], v35, off
	global_atomic_add_f32 v[32:33], v34, off offset:4

.LBB0_499:
	v_add_co_u32_e32 v30, vcc, 0x8000, v32
	v_cvt_pk_bf16_f32 v16, v26, v27
	v_cvt_pk_bf16_f32 v17, v28, v29
	v_cvt_pk_bf16_f32 v18, v20, v21
	v_cvt_pk_bf16_f32 v19, v22, v23
	s_nop 1
	v_addc_co_u32_e32 v31, vcc, 0, v33, vcc
	s_and_b64 vcc, exec, s[0:1]
	global_store_dwordx4 v[30:31], v[16:19], off
	s_cbranch_vccnz .LBB0_503
	s_nop 0
	v_add_f32_e32 v16, v26, v27
	v_add_f32_e32 v17, v28, v29
	v_add_f32_e32 v16, v16, v17
	v_add_f32_e32 v17, v20, v21
	v_add_f32_e32 v16, v16, v17
	v_add_f32_e32 v17, v22, v23
	v_add_f32_e32 v16, v17, v16
	v_mul_f32_e32 v17, v27, v27
	v_mul_f32_e32 v18, v29, v29
	v_fmac_f32_e32 v17, v26, v26
	v_fmac_f32_e32 v18, v28, v28
	v_add_f32_e32 v17, v17, v18
	v_mul_f32_e32 v18, v21, v21
	v_fmac_f32_e32 v18, v20, v20
	v_add_f32_e32 v17, v17, v18
	v_mul_f32_e32 v18, v23, v23
	v_fmac_f32_e32 v18, v22, v22
	v_add_f32_e32 v17, v18, v17
	v_add_f32_e32 v16, v24, v16
	v_add_f32_e32 v19, v25, v17
	v_mov_b32_e32 v18, v16
	s_nop 1
	v_permlane16_swap_b32_e32 v18, v16
	s_nop 0
	v_mov_b32_e32 v20, v19
	s_nop 1
	v_permlane16_swap_b32_e32 v20, v19
	s_nop 0
	s_waitcnt lgkmcnt(0)
	v_add_f32_e32 v16, v16, v18
	v_add_f32_e32 v18, v19, v20
	v_mov_b32_e32 v17, v16
	s_nop 1
	v_permlane32_swap_b32_e32 v17, v16
	s_nop 0
	v_mov_b32_e32 v19, v18
	s_nop 1
	v_permlane32_swap_b32_e32 v19, v18
	s_nop 0
	s_and_saveexec_b64 s[0:1], s[4:5]
	s_cbranch_execz .LBB0_502
	s_waitcnt lgkmcnt(0)
	v_add_f32_e32 v18, v18, v19
	v_add_f32_e32 v19, v16, v17
	v_add_u32_e32 v16, s21, v110
	v_ashrrev_i32_e32 v17, 31, v16
	v_lshl_add_u64 v[16:17], v[16:17], 3, s[72:73]
	global_atomic_add_f32 v[16:17], v19, off
	global_atomic_add_f32 v[16:17], v18, off offset:4

.LBB0_536:
	v_add_co_u32_e32 v14, vcc, 0x8000, v16
	v_cvt_pk_bf16_f32 v0, v10, v11
	v_cvt_pk_bf16_f32 v1, v12, v13
	v_cvt_pk_bf16_f32 v2, v4, v5
	v_cvt_pk_bf16_f32 v3, v6, v7
	s_nop 1
	v_addc_co_u32_e32 v15, vcc, 0, v17, vcc
	s_and_b64 vcc, exec, s[0:1]
	global_store_dwordx4 v[14:15], v[0:3], off
	s_cbranch_vccnz .LBB0_238
	s_nop 0
	v_add_f32_e32 v0, v10, v11
	v_add_f32_e32 v1, v12, v13
	v_add_f32_e32 v0, v0, v1
	v_add_f32_e32 v1, v4, v5
	v_add_f32_e32 v0, v0, v1
	v_add_f32_e32 v1, v6, v7
	v_add_f32_e32 v0, v1, v0
	v_mul_f32_e32 v1, v11, v11
	v_mul_f32_e32 v2, v13, v13
	v_fmac_f32_e32 v1, v10, v10
	v_fmac_f32_e32 v2, v12, v12
	v_add_f32_e32 v1, v1, v2
	v_mul_f32_e32 v2, v5, v5
	v_fmac_f32_e32 v2, v4, v4
	v_add_f32_e32 v1, v1, v2
	v_mul_f32_e32 v2, v7, v7
	v_fmac_f32_e32 v2, v6, v6
	v_add_f32_e32 v1, v2, v1
	v_add_f32_e32 v0, v8, v0
	v_add_f32_e32 v3, v9, v1
	v_mov_b32_e32 v2, v0
	s_nop 1
	v_permlane16_swap_b32_e32 v2, v0
	s_nop 0
	v_mov_b32_e32 v4, v3
	s_nop 1
	v_permlane16_swap_b32_e32 v4, v3
	s_nop 0
	s_waitcnt lgkmcnt(0)
	v_add_f32_e32 v0, v0, v2
	v_add_f32_e32 v2, v3, v4
	v_mov_b32_e32 v1, v0
	s_nop 1
	v_permlane32_swap_b32_e32 v1, v0
	s_nop 0
	v_mov_b32_e32 v3, v2
	s_nop 1
	v_permlane32_swap_b32_e32 v3, v2
	s_nop 0
	s_and_saveexec_b64 s[0:1], s[4:5]
	s_cbranch_execz .LBB0_237
	s_waitcnt lgkmcnt(0)
	v_add_f32_e32 v2, v2, v3
	v_add_f32_e32 v3, v0, v1
	v_add_u32_e32 v0, s21, v94
	v_ashrrev_i32_e32 v1, 31, v0
	v_lshl_add_u64 v[0:1], v[0:1], 3, s[72:73]
	global_atomic_add_f32 v[0:1], v3, off
	global_atomic_add_f32 v[0:1], v2, off offset:4
	s_branch .LBB0_237

.LBB0_903:
	s_barrier
	s_add_u32 s0, s78, 0xedc8000
	v_ashrrev_i32_e32 v190, 6, v202
	s_addc_u32 s1, s79, 0
	v_readfirstlane_b32 s3, v190
	s_and_b32 s6, s3, 3
	s_lshl_b32 s4, s13, 8
	s_lshl_b32 s5, s6, 5
	s_or_b32 s4, s5, s4
	v_lshrrev_b32_e32 v128, 2, v202
	v_and_or_b32 v188, v128, 12, s4
	s_lshl_b32 s4, s2, 7
	s_and_b32 s4, s4, 0xfffffc00
	s_ashr_i32 s5, s4, 31
	s_lshl_b64 s[4:5], s[4:5], 2
	v_readlane_b32 s7, v234, 21
	s_add_u32 s4, s7, s4
	v_readlane_b32 s7, v234, 20
	s_addc_u32 s5, s7, s5
	s_lshl_b32 s3, s3, 4
	s_andn2_b32 s3, s3, 63
	v_and_or_b32 v128, v202, 15, s3
	v_lshl_add_u32 v172, s2, 8, v128
	v_readlane_b32 s56, v234, 0
	v_ashrrev_i32_e32 v173, 31, v172
	v_readlane_b32 s57, v234, 1
	v_ashrrev_i32_e32 v189, 31, v188
	v_lshlrev_b64 v[146:147], 12, v[172:173]
	s_mov_b64 s[16:17], s[56:57]
	v_lshlrev_b64 v[144:145], 2, v[188:189]
	v_lshl_add_u64 v[128:129], s[16:17], 0, v[146:147]
	v_lshl_add_u64 v[136:137], s[4:5], 0, v[144:145]
	v_lshl_add_u64 v[160:161], v[128:129], 0, v[144:145]
	global_load_dwordx4 v[148:151], v[160:161], off
	global_load_dwordx4 v[132:135], v[136:137], off
	global_load_dwordx4 v[128:131], v[136:137], off offset:64
	global_load_dwordx4 v[152:155], v[160:161], off offset:64
	global_load_dwordx4 v[156:159], v[160:161], off offset:512
	global_load_dwordx4 v[140:143], v[136:137], off offset:512
	s_nop 0
	global_load_dwordx4 v[136:139], v[136:137], off offset:576
	s_nop 0
	global_load_dwordx4 v[160:163], v[160:161], off offset:576
	v_and_b32_e32 v191, 63, v202
	v_cmp_gt_u32_e32 vcc, 16, v191
	s_mov_b32 s5, 0
	v_lshlrev_b64 v[174:175], 6, v[172:173]
	v_readlane_b32 s58, v234, 2
	v_readlane_b32 s59, v234, 3
	v_readlane_b32 s60, v234, 4
	v_readlane_b32 s61, v234, 5
	v_readlane_b32 s62, v234, 6
	v_readlane_b32 s63, v234, 7
	v_readlane_b32 s64, v234, 8
	v_readlane_b32 s65, v234, 9
	v_readlane_b32 s66, v234, 10
	v_readlane_b32 s67, v234, 11
	v_readlane_b32 s68, v234, 12
	v_readlane_b32 s69, v234, 13
	v_readlane_b32 s70, v234, 14
	v_readlane_b32 s71, v234, 15
	s_waitcnt vmcnt(0)
	v_pk_fma_f32 v[126:127], v[126:127], v[134:135], v[150:151]
	v_pk_fma_f32 v[124:125], v[124:125], v[132:133], v[148:149]
	v_pk_fma_f32 v[122:123], v[122:123], v[130:131], v[154:155]
	v_pk_fma_f32 v[120:121], v[120:121], v[128:129], v[152:153]
	v_pk_fma_f32 v[118:119], v[118:119], v[142:143], v[158:159]
	v_pk_fma_f32 v[116:117], v[116:117], v[140:141], v[156:157]
	v_mul_f32_e32 v148, v125, v125
	v_mul_f32_e32 v149, v127, v127
	v_mul_f32_e32 v150, v121, v121
	v_mul_f32_e32 v151, v123, v123
	v_pk_fma_f32 v[114:115], v[114:115], v[138:139], v[162:163]
	v_pk_fma_f32 v[112:113], v[112:113], v[136:137], v[160:161]
	v_mul_f32_e32 v152, v117, v117
	v_mul_f32_e32 v153, v119, v119
	v_fmac_f32_e32 v148, v124, v124
	v_fmac_f32_e32 v149, v126, v126
	v_fmac_f32_e32 v150, v120, v120
	v_fmac_f32_e32 v151, v122, v122
	v_mul_f32_e32 v154, v113, v113
	v_mul_f32_e32 v155, v115, v115
	v_fmac_f32_e32 v152, v116, v116
	v_fmac_f32_e32 v153, v118, v118
	v_add_f32_e32 v148, v148, v149
	v_add_f32_e32 v149, v150, v151
	v_fmac_f32_e32 v154, v112, v112
	v_fmac_f32_e32 v155, v114, v114
	v_add_f32_e32 v150, v152, v153
	v_add_f32_e32 v148, v148, v149
	v_add_f32_e32 v148, v148, v150
	v_add_f32_e32 v149, v154, v155
	v_add_f32_e32 v148, v148, v149
	v_mov_b32_e32 v149, v148
	s_nop 1
	v_permlane16_swap_b32_e32 v149, v148
	s_nop 0
	s_waitcnt lgkmcnt(0)
	v_add_f32_e32 v148, v148, v149
	v_mov_b32_e32 v149, v148
	s_nop 1
	v_permlane32_swap_b32_e32 v149, v148
	s_nop 0
	s_and_saveexec_b64 s[2:3], vcc
	v_readlane_b32 s24, v234, 45
	v_readlane_b32 s14, v234, 49
	v_readlane_b32 s25, v234, 46
	v_readlane_b32 s15, v234, 50
	s_cbranch_execz .LBB0_905
	s_lshl_b32 s8, s13, 2
	s_waitcnt lgkmcnt(0)
	v_add_f32_e32 v150, v148, v149
	s_ashr_i32 s9, s8, 31
	v_lshl_add_u64 v[148:149], s[0:1], 0, v[174:175]
	v_lshl_add_u64 v[148:149], s[8:9], 2, v[148:149]
	s_lshl_b32 s4, s6, 2
	v_lshl_add_u64 v[148:149], v[148:149], 0, s[4:5]
	global_store_dword v[148:149], v150, off
.LBB0_905:
	s_or_b64 exec, exec, s[2:3]
	v_or_b32_e32 v166, 16, v172
	v_ashrrev_i32_e32 v167, 31, v166
	s_waitcnt lgkmcnt(0)
	v_lshlrev_b64 v[148:149], 12, v[166:167]
	v_lshl_add_u64 v[150:151], s[16:17], 0, v[148:149]
	v_lshl_add_u64 v[162:163], v[188:189], 2, v[150:151]
	global_load_dwordx4 v[150:153], v[162:163], off
	global_load_dwordx4 v[154:157], v[162:163], off offset:64
	global_load_dwordx4 v[158:161], v[162:163], off offset:512
	s_nop 0
	global_load_dwordx4 v[162:165], v[162:163], off offset:576
	v_lshlrev_b64 v[176:177], 6, v[166:167]
	s_waitcnt vmcnt(3)
	v_pk_fma_f32 v[110:111], v[110:111], v[134:135], v[152:153]
	v_pk_fma_f32 v[108:109], v[108:109], v[132:133], v[150:151]
	s_waitcnt vmcnt(2)
	v_pk_fma_f32 v[106:107], v[106:107], v[130:131], v[156:157]
	v_pk_fma_f32 v[104:105], v[104:105], v[128:129], v[154:155]
	s_waitcnt vmcnt(1)
	v_pk_fma_f32 v[102:103], v[102:103], v[142:143], v[160:161]
	v_pk_fma_f32 v[100:101], v[100:101], v[140:141], v[158:159]
	v_mul_f32_e32 v150, v109, v109
	v_mul_f32_e32 v151, v111, v111
	v_mul_f32_e32 v152, v105, v105
	v_mul_f32_e32 v153, v107, v107
	s_waitcnt vmcnt(0)
	v_pk_fma_f32 v[98:99], v[98:99], v[138:139], v[164:165]
	v_pk_fma_f32 v[96:97], v[96:97], v[136:137], v[162:163]
	v_mul_f32_e32 v154, v101, v101
	v_mul_f32_e32 v155, v103, v103
	v_fmac_f32_e32 v150, v108, v108
	v_fmac_f32_e32 v151, v110, v110
	v_fmac_f32_e32 v152, v104, v104
	v_fmac_f32_e32 v153, v106, v106
	v_mul_f32_e32 v156, v97, v97
	v_mul_f32_e32 v157, v99, v99
	v_fmac_f32_e32 v154, v100, v100
	v_fmac_f32_e32 v155, v102, v102
	v_add_f32_e32 v150, v150, v151
	v_add_f32_e32 v151, v152, v153
	v_fmac_f32_e32 v156, v96, v96
	v_fmac_f32_e32 v157, v98, v98
	v_add_f32_e32 v152, v154, v155
	v_add_f32_e32 v150, v150, v151
	v_add_f32_e32 v150, v150, v152
	v_add_f32_e32 v151, v156, v157
	v_add_f32_e32 v150, v150, v151
	v_mov_b32_e32 v151, v150
	s_nop 1
	v_permlane16_swap_b32_e32 v151, v150
	s_nop 0
	s_waitcnt lgkmcnt(0)
	v_add_f32_e32 v150, v150, v151
	v_mov_b32_e32 v151, v150
	s_nop 1
	v_permlane32_swap_b32_e32 v151, v150
	s_nop 0
	s_and_saveexec_b64 s[2:3], vcc
	s_cbranch_execz .LBB0_907
	s_lshl_b32 s4, s13, 2
	s_waitcnt lgkmcnt(0)
	v_add_f32_e32 v152, v150, v151
	s_ashr_i32 s5, s4, 31
	v_lshl_add_u64 v[150:151], s[0:1], 0, v[176:177]
	v_lshl_add_u64 v[150:151], s[4:5], 2, v[150:151]
	s_lshl_b32 s4, s6, 2
	s_mov_b32 s5, 0
	v_lshl_add_u64 v[150:151], v[150:151], 0, s[4:5]
	global_store_dword v[150:151], v152, off
.LBB0_907:
	s_or_b64 exec, exec, s[2:3]
	v_or_b32_e32 v168, 32, v172
	v_ashrrev_i32_e32 v169, 31, v168
	s_waitcnt lgkmcnt(0)
	v_lshlrev_b64 v[150:151], 12, v[168:169]
	v_lshl_add_u64 v[152:153], s[16:17], 0, v[150:151]
	v_lshl_add_u64 v[164:165], v[188:189], 2, v[152:153]
	global_load_dwordx4 v[152:155], v[164:165], off
	global_load_dwordx4 v[156:159], v[164:165], off offset:64
	global_load_dwordx4 v[160:163], v[164:165], off offset:512
	s_nop 0
	global_load_dwordx4 v[164:167], v[164:165], off offset:576
	v_lshlrev_b64 v[178:179], 6, v[168:169]
	s_waitcnt vmcnt(3)
	v_pk_fma_f32 v[94:95], v[94:95], v[134:135], v[154:155]
	v_pk_fma_f32 v[92:93], v[92:93], v[132:133], v[152:153]
	s_waitcnt vmcnt(2)
	v_pk_fma_f32 v[90:91], v[90:91], v[130:131], v[158:159]
	v_pk_fma_f32 v[88:89], v[88:89], v[128:129], v[156:157]
	s_waitcnt vmcnt(1)
	v_pk_fma_f32 v[86:87], v[86:87], v[142:143], v[162:163]
	v_pk_fma_f32 v[84:85], v[84:85], v[140:141], v[160:161]
	v_mul_f32_e32 v152, v93, v93
	v_mul_f32_e32 v153, v95, v95
	v_mul_f32_e32 v154, v89, v89
	v_mul_f32_e32 v155, v91, v91
	s_waitcnt vmcnt(0)
	v_pk_fma_f32 v[82:83], v[82:83], v[138:139], v[166:167]
	v_pk_fma_f32 v[80:81], v[80:81], v[136:137], v[164:165]
	v_mul_f32_e32 v156, v85, v85
	v_mul_f32_e32 v157, v87, v87
	v_fmac_f32_e32 v152, v92, v92
	v_fmac_f32_e32 v153, v94, v94
	v_fmac_f32_e32 v154, v88, v88
	v_fmac_f32_e32 v155, v90, v90
	v_mul_f32_e32 v158, v81, v81
	v_mul_f32_e32 v159, v83, v83
	v_fmac_f32_e32 v156, v84, v84
	v_fmac_f32_e32 v157, v86, v86
	v_add_f32_e32 v152, v152, v153
	v_add_f32_e32 v153, v154, v155
	v_fmac_f32_e32 v158, v80, v80
	v_fmac_f32_e32 v159, v82, v82
	v_add_f32_e32 v154, v156, v157
	v_add_f32_e32 v152, v152, v153
	v_add_f32_e32 v152, v152, v154
	v_add_f32_e32 v153, v158, v159
	v_add_f32_e32 v152, v152, v153
	v_mov_b32_e32 v153, v152
	s_nop 1
	v_permlane16_swap_b32_e32 v153, v152
	s_nop 0
	s_waitcnt lgkmcnt(0)
	v_add_f32_e32 v152, v152, v153
	v_mov_b32_e32 v153, v152
	s_nop 1
	v_permlane32_swap_b32_e32 v153, v152
	s_nop 0
	s_and_saveexec_b64 s[2:3], vcc
	s_cbranch_execz .LBB0_909
	s_lshl_b32 s4, s13, 2
	s_waitcnt lgkmcnt(0)
	v_add_f32_e32 v154, v152, v153
	s_ashr_i32 s5, s4, 31
	v_lshl_add_u64 v[152:153], s[0:1], 0, v[178:179]
	v_lshl_add_u64 v[152:153], s[4:5], 2, v[152:153]
	s_lshl_b32 s4, s6, 2
	s_mov_b32 s5, 0
	v_lshl_add_u64 v[152:153], v[152:153], 0, s[4:5]
	global_store_dword v[152:153], v154, off
.LBB0_909:
	s_or_b64 exec, exec, s[2:3]
	v_or_b32_e32 v170, 48, v172
	v_ashrrev_i32_e32 v171, 31, v170
	s_waitcnt lgkmcnt(0)
	v_lshlrev_b64 v[152:153], 12, v[170:171]
	v_lshl_add_u64 v[154:155], s[16:17], 0, v[152:153]
	v_lshl_add_u64 v[166:167], v[188:189], 2, v[154:155]
	global_load_dwordx4 v[154:157], v[166:167], off
	global_load_dwordx4 v[158:161], v[166:167], off offset:64
	global_load_dwordx4 v[162:165], v[166:167], off offset:512
	s_nop 0
	global_load_dwordx4 v[166:169], v[166:167], off offset:576
	v_lshlrev_b64 v[180:181], 6, v[170:171]
	s_waitcnt vmcnt(3)
	v_pk_fma_f32 v[78:79], v[78:79], v[134:135], v[156:157]
	v_pk_fma_f32 v[76:77], v[76:77], v[132:133], v[154:155]
	s_waitcnt vmcnt(2)
	v_pk_fma_f32 v[74:75], v[74:75], v[130:131], v[160:161]
	v_pk_fma_f32 v[72:73], v[72:73], v[128:129], v[158:159]
	s_waitcnt vmcnt(1)
	v_pk_fma_f32 v[70:71], v[70:71], v[142:143], v[164:165]
	v_pk_fma_f32 v[68:69], v[68:69], v[140:141], v[162:163]
	v_mul_f32_e32 v154, v77, v77
	v_mul_f32_e32 v155, v79, v79
	v_mul_f32_e32 v156, v73, v73
	v_mul_f32_e32 v157, v75, v75
	s_waitcnt vmcnt(0)
	v_pk_fma_f32 v[66:67], v[66:67], v[138:139], v[168:169]
	v_pk_fma_f32 v[64:65], v[64:65], v[136:137], v[166:167]
	v_mul_f32_e32 v158, v69, v69
	v_mul_f32_e32 v159, v71, v71
	v_fmac_f32_e32 v154, v76, v76
	v_fmac_f32_e32 v155, v78, v78
	v_fmac_f32_e32 v156, v72, v72
	v_fmac_f32_e32 v157, v74, v74
	v_mul_f32_e32 v160, v65, v65
	v_mul_f32_e32 v161, v67, v67
	v_fmac_f32_e32 v158, v68, v68
	v_fmac_f32_e32 v159, v70, v70
	v_add_f32_e32 v154, v154, v155
	v_add_f32_e32 v155, v156, v157
	v_fmac_f32_e32 v160, v64, v64
	v_fmac_f32_e32 v161, v66, v66
	v_add_f32_e32 v156, v158, v159
	v_add_f32_e32 v154, v154, v155
	v_add_f32_e32 v154, v154, v156
	v_add_f32_e32 v155, v160, v161
	v_add_f32_e32 v154, v154, v155
	v_mov_b32_e32 v155, v154
	s_nop 1
	v_permlane16_swap_b32_e32 v155, v154
	s_nop 0
	s_waitcnt lgkmcnt(0)
	v_add_f32_e32 v154, v154, v155
	v_mov_b32_e32 v155, v154
	s_nop 1
	v_permlane32_swap_b32_e32 v155, v154
	s_nop 0
	s_and_saveexec_b64 s[2:3], vcc
	s_cbranch_execz .LBB0_911
	s_lshl_b32 s4, s13, 2
	s_waitcnt lgkmcnt(0)
	v_add_f32_e32 v156, v154, v155
	s_ashr_i32 s5, s4, 31
	v_lshl_add_u64 v[154:155], s[0:1], 0, v[180:181]
	v_lshl_add_u64 v[154:155], s[4:5], 2, v[154:155]
	s_lshl_b32 s4, s6, 2
	s_mov_b32 s5, 0
	v_lshl_add_u64 v[154:155], v[154:155], 0, s[4:5]
	global_store_dword v[154:155], v156, off
.LBB0_911:
	s_or_b64 exec, exec, s[2:3]
	v_add_u32_e32 v182, 0x80, v172
	v_ashrrev_i32_e32 v183, 31, v182
	s_waitcnt lgkmcnt(0)
	v_lshlrev_b64 v[154:155], 12, v[182:183]
	v_lshl_add_u64 v[156:157], s[16:17], 0, v[154:155]
	v_lshl_add_u64 v[168:169], v[188:189], 2, v[156:157]
	global_load_dwordx4 v[156:159], v[168:169], off
	global_load_dwordx4 v[160:163], v[168:169], off offset:64
	global_load_dwordx4 v[164:167], v[168:169], off offset:512
	s_nop 0
	global_load_dwordx4 v[168:171], v[168:169], off offset:576
	v_lshlrev_b64 v[182:183], 6, v[182:183]
	s_waitcnt vmcnt(3)
	v_pk_fma_f32 v[62:63], v[62:63], v[134:135], v[158:159]
	v_pk_fma_f32 v[60:61], v[60:61], v[132:133], v[156:157]
	s_waitcnt vmcnt(2)
	v_pk_fma_f32 v[58:59], v[58:59], v[130:131], v[162:163]
	v_pk_fma_f32 v[56:57], v[56:57], v[128:129], v[160:161]
	s_waitcnt vmcnt(1)
	v_pk_fma_f32 v[54:55], v[54:55], v[142:143], v[166:167]
	v_pk_fma_f32 v[52:53], v[52:53], v[140:141], v[164:165]
	v_mul_f32_e32 v156, v61, v61
	v_mul_f32_e32 v157, v63, v63
	v_mul_f32_e32 v158, v57, v57
	v_mul_f32_e32 v159, v59, v59
	s_waitcnt vmcnt(0)
	v_pk_fma_f32 v[50:51], v[50:51], v[138:139], v[170:171]
	v_pk_fma_f32 v[48:49], v[48:49], v[136:137], v[168:169]
	v_mul_f32_e32 v160, v53, v53
	v_mul_f32_e32 v161, v55, v55
	v_fmac_f32_e32 v156, v60, v60
	v_fmac_f32_e32 v157, v62, v62
	v_fmac_f32_e32 v158, v56, v56
	v_fmac_f32_e32 v159, v58, v58
	v_mul_f32_e32 v162, v49, v49
	v_mul_f32_e32 v163, v51, v51
	v_fmac_f32_e32 v160, v52, v52
	v_fmac_f32_e32 v161, v54, v54
	v_add_f32_e32 v156, v156, v157
	v_add_f32_e32 v157, v158, v159
	v_fmac_f32_e32 v162, v48, v48
	v_fmac_f32_e32 v163, v50, v50
	v_add_f32_e32 v158, v160, v161
	v_add_f32_e32 v156, v156, v157
	v_add_f32_e32 v156, v156, v158
	v_add_f32_e32 v157, v162, v163
	v_add_f32_e32 v156, v156, v157
	v_mov_b32_e32 v157, v156
	s_nop 1
	v_permlane16_swap_b32_e32 v157, v156
	s_nop 0
	s_waitcnt lgkmcnt(0)
	v_add_f32_e32 v156, v156, v157
	v_mov_b32_e32 v157, v156
	s_nop 1
	v_permlane32_swap_b32_e32 v157, v156
	s_nop 0
	s_and_saveexec_b64 s[2:3], vcc
	s_cbranch_execz .LBB0_913
	s_lshl_b32 s4, s13, 2
	s_waitcnt lgkmcnt(0)
	v_add_f32_e32 v158, v156, v157
	s_ashr_i32 s5, s4, 31
	v_lshl_add_u64 v[156:157], s[0:1], 0, v[182:183]
	v_lshl_add_u64 v[156:157], s[4:5], 2, v[156:157]
	s_lshl_b32 s4, s6, 2
	s_mov_b32 s5, 0
	v_lshl_add_u64 v[156:157], v[156:157], 0, s[4:5]
	global_store_dword v[156:157], v158, off
.LBB0_913:
	s_or_b64 exec, exec, s[2:3]
	v_add_u32_e32 v170, 0x90, v172
	v_ashrrev_i32_e32 v171, 31, v170
	s_waitcnt lgkmcnt(0)
	v_lshlrev_b64 v[156:157], 12, v[170:171]
	v_lshl_add_u64 v[158:159], s[16:17], 0, v[156:157]
	v_lshl_add_u64 v[184:185], v[188:189], 2, v[158:159]
	global_load_dwordx4 v[158:161], v[184:185], off
	global_load_dwordx4 v[162:165], v[184:185], off offset:64
	global_load_dwordx4 v[166:169], v[184:185], off offset:512
	s_nop 0
	global_load_dwordx4 v[184:187], v[184:185], off offset:576
	s_waitcnt vmcnt(3)
	v_pk_fma_f32 v[46:47], v[46:47], v[134:135], v[160:161]
	v_pk_fma_f32 v[44:45], v[44:45], v[132:133], v[158:159]
	s_waitcnt vmcnt(2)
	v_pk_fma_f32 v[42:43], v[42:43], v[130:131], v[164:165]
	v_pk_fma_f32 v[40:41], v[40:41], v[128:129], v[162:163]
	s_waitcnt vmcnt(1)
	v_pk_fma_f32 v[38:39], v[38:39], v[142:143], v[168:169]
	v_pk_fma_f32 v[36:37], v[36:37], v[140:141], v[166:167]
	v_mul_f32_e32 v158, v45, v45
	v_mul_f32_e32 v159, v47, v47
	v_mul_f32_e32 v160, v41, v41
	v_mul_f32_e32 v161, v43, v43
	s_waitcnt vmcnt(0)
	v_pk_fma_f32 v[34:35], v[34:35], v[138:139], v[186:187]
	v_pk_fma_f32 v[32:33], v[32:33], v[136:137], v[184:185]
	v_mul_f32_e32 v162, v37, v37
	v_mul_f32_e32 v163, v39, v39
	v_fmac_f32_e32 v158, v44, v44
	v_fmac_f32_e32 v159, v46, v46
	v_fmac_f32_e32 v160, v40, v40
	v_fmac_f32_e32 v161, v42, v42
	v_mul_f32_e32 v164, v33, v33
	v_mul_f32_e32 v165, v35, v35
	v_fmac_f32_e32 v162, v36, v36
	v_fmac_f32_e32 v163, v38, v38
	v_add_f32_e32 v158, v158, v159
	v_add_f32_e32 v159, v160, v161
	v_fmac_f32_e32 v164, v32, v32
	v_fmac_f32_e32 v165, v34, v34
	v_add_f32_e32 v160, v162, v163
	v_add_f32_e32 v158, v158, v159
	v_add_f32_e32 v158, v158, v160
	v_add_f32_e32 v159, v164, v165
	v_add_f32_e32 v158, v158, v159
	v_mov_b32_e32 v159, v158
	s_nop 1
	v_permlane16_swap_b32_e32 v159, v158
	s_nop 0
	v_lshlrev_b64 v[184:185], 6, v[170:171]
	s_waitcnt lgkmcnt(0)
	v_add_f32_e32 v158, v158, v159
	v_mov_b32_e32 v159, v158
	s_nop 1
	v_permlane32_swap_b32_e32 v159, v158
	s_nop 0
	s_and_saveexec_b64 s[2:3], vcc
	s_cbranch_execz .LBB0_915
	s_lshl_b32 s4, s13, 2
	s_waitcnt lgkmcnt(0)
	v_add_f32_e32 v160, v158, v159
	s_ashr_i32 s5, s4, 31
	v_lshl_add_u64 v[158:159], s[0:1], 0, v[184:185]
	v_lshl_add_u64 v[158:159], s[4:5], 2, v[158:159]
	s_lshl_b32 s4, s6, 2
	s_mov_b32 s5, 0
	v_lshl_add_u64 v[158:159], v[158:159], 0, s[4:5]
	global_store_dword v[158:159], v160, off
.LBB0_915:
	s_or_b64 exec, exec, s[2:3]
	v_add_u32_e32 v186, 0xa0, v172
	v_ashrrev_i32_e32 v187, 31, v186
	s_waitcnt lgkmcnt(0)
	v_lshlrev_b64 v[158:159], 12, v[186:187]
	v_lshl_add_u64 v[160:161], s[16:17], 0, v[158:159]
	v_lshl_add_u64 v[160:161], v[188:189], 2, v[160:161]
	global_load_dwordx4 v[162:165], v[160:161], off
	global_load_dwordx4 v[168:171], v[160:161], off offset:64
	global_load_dwordx4 v[192:195], v[160:161], off offset:512
	global_load_dwordx4 v[196:199], v[160:161], off offset:576
	v_lshlrev_b64 v[186:187], 6, v[186:187]
	s_waitcnt vmcnt(3)
	v_pk_fma_f32 v[160:161], v[30:31], v[134:135], v[164:165]
	v_pk_fma_f32 v[166:167], v[28:29], v[132:133], v[162:163]
	s_waitcnt vmcnt(2)
	v_pk_fma_f32 v[30:31], v[26:27], v[130:131], v[170:171]
	v_pk_fma_f32 v[164:165], v[24:25], v[128:129], v[168:169]
	s_waitcnt vmcnt(1)
	v_pk_fma_f32 v[28:29], v[22:23], v[142:143], v[194:195]
	v_pk_fma_f32 v[162:163], v[20:21], v[140:141], v[192:193]
	s_waitcnt vmcnt(0)
	v_pk_fma_f32 v[168:169], v[18:19], v[138:139], v[198:199]
	v_pk_fma_f32 v[170:171], v[16:17], v[136:137], v[196:197]
	v_mul_f32_e32 v16, v167, v167
	v_mul_f32_e32 v17, v161, v161
	v_mul_f32_e32 v18, v165, v165
	v_mul_f32_e32 v19, v31, v31
	v_mul_f32_e32 v20, v163, v163
	v_mul_f32_e32 v21, v29, v29
	v_fmac_f32_e32 v16, v166, v166
	v_fmac_f32_e32 v17, v160, v160
	v_fmac_f32_e32 v18, v164, v164
	v_fmac_f32_e32 v19, v30, v30
	v_mul_f32_e32 v22, v171, v171
	v_mul_f32_e32 v23, v169, v169
	v_fmac_f32_e32 v20, v162, v162
	v_fmac_f32_e32 v21, v28, v28
	v_add_f32_e32 v16, v16, v17
	v_add_f32_e32 v17, v18, v19
	v_fmac_f32_e32 v22, v170, v170
	v_fmac_f32_e32 v23, v168, v168
	v_add_f32_e32 v18, v20, v21
	v_add_f32_e32 v16, v16, v17
	v_add_f32_e32 v16, v16, v18
	v_add_f32_e32 v17, v22, v23
	v_add_f32_e32 v16, v16, v17
	v_mov_b32_e32 v17, v16
	s_nop 1
	v_permlane16_swap_b32_e32 v17, v16
	s_nop 0
	s_waitcnt lgkmcnt(0)
	v_add_f32_e32 v16, v16, v17
	v_mov_b32_e32 v17, v16
	s_nop 1
	v_permlane32_swap_b32_e32 v17, v16
	s_nop 0
	s_and_saveexec_b64 s[2:3], vcc
	s_cbranch_execz .LBB0_917
	s_lshl_b32 s4, s13, 2
	s_waitcnt lgkmcnt(0)
	v_add_f32_e32 v18, v16, v17
	s_ashr_i32 s5, s4, 31
	v_lshl_add_u64 v[16:17], s[0:1], 0, v[186:187]
	v_lshl_add_u64 v[16:17], s[4:5], 2, v[16:17]
	s_lshl_b32 s4, s6, 2
	s_mov_b32 s5, 0
	v_lshl_add_u64 v[16:17], v[16:17], 0, s[4:5]
	global_store_dword v[16:17], v18, off
.LBB0_917:
	s_or_b64 exec, exec, s[2:3]
	v_add_u32_e32 v200, 0xb0, v172
	v_ashrrev_i32_e32 v201, 31, v200
	v_lshlrev_b64 v[172:173], 12, v[200:201]
	s_waitcnt lgkmcnt(0)
	v_lshl_add_u64 v[16:17], s[16:17], 0, v[172:173]
	v_lshl_add_u64 v[20:21], v[188:189], 2, v[16:17]
	global_load_dwordx4 v[16:19], v[20:21], off
	global_load_dwordx4 v[22:25], v[20:21], off offset:64
	global_load_dwordx4 v[192:195], v[20:21], off offset:512
	global_load_dwordx4 v[196:199], v[20:21], off offset:576
	s_waitcnt vmcnt(3)
	v_pk_fma_f32 v[20:21], v[14:15], v[134:135], v[18:19]
	v_pk_fma_f32 v[26:27], v[12:13], v[132:133], v[16:17]
	s_waitcnt vmcnt(2)
	v_pk_fma_f32 v[18:19], v[10:11], v[130:131], v[24:25]
	v_pk_fma_f32 v[24:25], v[8:9], v[128:129], v[22:23]
	s_waitcnt vmcnt(1)
	v_pk_fma_f32 v[16:17], v[6:7], v[142:143], v[194:195]
	v_pk_fma_f32 v[22:23], v[4:5], v[140:141], v[192:193]
	s_waitcnt vmcnt(0)
	v_pk_fma_f32 v[128:129], v[2:3], v[138:139], v[198:199]
	v_pk_fma_f32 v[130:131], v[0:1], v[136:137], v[196:197]
	v_mul_f32_e32 v0, v27, v27
	v_mul_f32_e32 v1, v21, v21
	v_mul_f32_e32 v2, v25, v25
	v_mul_f32_e32 v3, v19, v19
	v_mul_f32_e32 v4, v23, v23
	v_mul_f32_e32 v5, v17, v17
	v_fmac_f32_e32 v0, v26, v26
	v_fmac_f32_e32 v1, v20, v20
	v_fmac_f32_e32 v2, v24, v24
	v_fmac_f32_e32 v3, v18, v18
	v_mul_f32_e32 v6, v131, v131
	v_mul_f32_e32 v7, v129, v129
	v_fmac_f32_e32 v4, v22, v22
	v_fmac_f32_e32 v5, v16, v16
	v_add_f32_e32 v0, v0, v1
	v_add_f32_e32 v1, v2, v3
	v_fmac_f32_e32 v6, v130, v130
	v_fmac_f32_e32 v7, v128, v128
	v_add_f32_e32 v2, v4, v5
	v_add_f32_e32 v0, v0, v1
	v_add_f32_e32 v0, v0, v2
	v_add_f32_e32 v1, v6, v7
	v_add_f32_e32 v0, v0, v1
	v_mov_b32_e32 v1, v0
	s_nop 1
	v_permlane16_swap_b32_e32 v1, v0
	s_nop 0
	v_lshlrev_b64 v[132:133], 6, v[200:201]
	s_waitcnt lgkmcnt(0)
	v_add_f32_e32 v0, v0, v1
	v_mov_b32_e32 v1, v0
	s_nop 1
	v_permlane32_swap_b32_e32 v1, v0
	s_nop 0
	s_and_saveexec_b64 s[2:3], vcc
	s_cbranch_execz .LBB0_919
	s_lshl_b32 s4, s13, 2
	s_waitcnt lgkmcnt(0)
	v_add_f32_e32 v2, v0, v1
	s_ashr_i32 s5, s4, 31
	v_lshl_add_u64 v[0:1], s[0:1], 0, v[132:133]
	v_lshl_add_u64 v[0:1], s[4:5], 2, v[0:1]
	s_lshl_b32 s4, s6, 2
	s_mov_b32 s5, 0
	v_lshl_add_u64 v[0:1], v[0:1], 0, s[4:5]
	global_store_dword v[0:1], v2, off
